# P8a: workgroup->item position permuted so one XCD's 32 workgroups take 32 consecutive items per round (L2 reuse of window rows)
# speedup vs baseline: 1.0048x; 1.0048x over previous
.LBB0_1642:
	s_or_b64 exec, exec, s[0:1]
	v_readlane_b32 s0, v254, 50
	s_cmpk_lt_i32 s0, 0x880
	s_waitcnt lgkmcnt(0)
	v_mov_b32_e32 v0, v250
	s_barrier
	v_readlane_b32 s1, v254, 51
	s_cbranch_scc0 .LBB0_1974
	v_lshlrev_b32_e32 v76, 2, v0
	v_ashrrev_i32_e32 v77, 31, v76
	s_add_u32 s12, s50, 0x2914d700
	v_add_u32_e32 v2, 0x800, v76
	v_lshlrev_b64 v[80:81], 2, v[76:77]
	s_movk_i32 s0, 0x7f
	v_mov_b32_e32 v91, 0
	v_mov_b32_e32 v90, v76
	v_ashrrev_i32_e32 v100, 7, v0
	s_addc_u32 s13, s51, 0
	v_ashrrev_i32_e32 v3, 31, v2
	v_lshlrev_b64 v[4:5], 1, v[76:77]
	v_lshl_add_u64 v[82:83], s[4:5], 0, v[80:81]
	v_cmp_lt_u32_e64 s[4:5], s0, v0
	v_lshlrev_b64 v[0:1], 2, v[90:91]
	v_readlane_b32 s0, v254, 50
	v_lshl_add_u64 v[78:79], s[38:39], 0, v[4:5]
	v_lshl_add_u64 v[84:85], s[56:57], 0, v[80:81]
	v_lshl_add_u64 v[86:87], s[6:7], 0, v[80:81]
	v_lshl_add_u64 v[88:89], s[12:13], 0, v[4:5]
	v_lshl_add_u64 v[92:93], s[56:57], 0, v[0:1]
	v_lshl_add_u64 v[94:95], s[6:7], 0, v[0:1]
	v_lshl_add_u64 v[96:97], v[90:91], 1, s[12:13]
	v_lshlrev_b64 v[98:99], 2, v[2:3]
	s_mov_b32 s21, 0
	s_mov_b32 s22, 0x3e800000
	v_mov_b32_e32 v101, 0x3e000000
	v_mov_b32_e32 v102, 0x3d800000
	v_mov_b32_e32 v103, 0x3e800000
	s_mov_b32 s2, s0
	v_readlane_b32 s1, v254, 51
	s_cmpk_eq_u32 s92, 0x100
	s_cbranch_scc0 .Lp8a_nomap
	s_and_b32 s98, s0, 7
	s_lshr_b32 s99, s0, 3
	s_lshl_b32 s98, s98, 5
	s_add_i32 s2, s98, s99
	s_lshl_b32 s18, s2, 2
.Lp8a_nomap:
	s_branch .LBB0_1646
.LBB0_1644:
	s_and_b64 s[0:1], s[10:11], exec
	s_cselect_b32 s0, 1.0, 0.5
	v_mov_b32_e32 v24, s0
	s_waitcnt vmcnt(0)
	v_pk_add_f32 v[20:21], v[2:3], v[6:7]
	v_pk_add_f32 v[22:23], v[0:1], v[4:5]
	v_cndmask_b32_e64 v24, 0.5, v24, s[6:7]
	v_xor_b32_e32 v27, 0x80000000, v7
	v_xor_b32_e32 v26, 0x80000000, v6
	s_ashr_i32 s19, s18, 31
	v_pk_fma_f32 v[26:27], v[24:25], v[20:21], v[26:27] op_sel_hi:[0,1,1]
	v_pk_fma_f32 v[24:25], v[24:25], v[22:23], v[4:5] op_sel_hi:[0,1,1] neg_lo:[0,0,1] neg_hi:[0,0,1]
	s_lshl_b64 s[0:1], s[18:19], 12
	v_cvt_pk_bf16_f32 v24, v24, v25
	v_cvt_pk_bf16_f32 v25, v26, v27
	v_lshl_add_u64 v[26:27], v[96:97], 0, s[0:1]
	v_sub_f32_e32 v1, v9, v1
	v_sub_f32_e32 v0, v8, v0
	v_sub_f32_e32 v3, v11, v3
	v_sub_f32_e32 v2, v10, v2
	s_add_i32 s0, s18, 1
	v_pk_add_f32 v[2:3], v[20:21], v[2:3]
	v_pk_add_f32 v[0:1], v[22:23], v[0:1]
	v_xor_b32_e32 v21, 0x80000000, v11
	v_xor_b32_e32 v20, 0x80000000, v10
	s_ashr_i32 s1, s0, 31
	v_pk_fma_f32 v[20:21], v[2:3], 0.5, v[20:21] op_sel_hi:[1,0,1]
	v_pk_fma_f32 v[22:23], v[0:1], 0.5, v[8:9] op_sel_hi:[1,0,1] neg_lo:[0,0,1] neg_hi:[0,0,1]
	s_lshl_b64 s[0:1], s[0:1], 12
	v_cvt_pk_bf16_f32 v22, v22, v23
	v_cvt_pk_bf16_f32 v23, v20, v21
	v_lshl_add_u64 v[20:21], v[96:97], 0, s[0:1]
	v_sub_f32_e32 v7, v15, v7
	v_sub_f32_e32 v6, v14, v6
	v_sub_f32_e32 v5, v13, v5
	v_sub_f32_e32 v4, v12, v4
	s_add_i32 s0, s18, 2
	v_pk_add_f32 v[0:1], v[0:1], v[4:5]
	v_pk_add_f32 v[2:3], v[2:3], v[6:7]
	v_xor_b32_e32 v5, 0x80000000, v15
	v_xor_b32_e32 v4, 0x80000000, v14
	s_ashr_i32 s1, s0, 31
	v_pk_fma_f32 v[4:5], v[2:3], 0.5, v[4:5] op_sel_hi:[1,0,1]
	v_pk_fma_f32 v[6:7], v[0:1], 0.5, v[12:13] op_sel_hi:[1,0,1] neg_lo:[0,0,1] neg_hi:[0,0,1]
	s_lshl_b64 s[0:1], s[0:1], 12
	v_cvt_pk_bf16_f32 v6, v6, v7
	v_cvt_pk_bf16_f32 v7, v4, v5
	v_lshl_add_u64 v[4:5], v[96:97], 0, s[0:1]
	global_store_dwordx2 v[4:5], v[6:7], off
	v_sub_f32_e32 v5, v19, v11
	v_sub_f32_e32 v4, v18, v10
	v_sub_f32_e32 v7, v17, v9
	v_sub_f32_e32 v6, v16, v8
	v_pk_add_f32 v[0:1], v[0:1], v[6:7]
	v_pk_add_f32 v[2:3], v[2:3], v[4:5]
	v_xor_b32_e32 v5, 0x80000000, v19
	v_xor_b32_e32 v4, 0x80000000, v18
	v_pk_fma_f32 v[2:3], v[2:3], 0.5, v[4:5] op_sel_hi:[1,0,1]
	v_pk_fma_f32 v[0:1], v[0:1], 0.5, v[16:17] op_sel_hi:[1,0,1] neg_lo:[0,0,1] neg_hi:[0,0,1]
	v_mov_b64_e32 v[4:5], v[90:91]
	global_store_dwordx2 v[26:27], v[24:25], off
	global_store_dwordx2 v[20:21], v[22:23], off
